# P10 norm-weight loads moved further up, to the start of the unit's final MFMA block (own address pair; that block's counted waits raised by four)
# baseline (speedup 1.0000x reference)
.LBB0_978:
	s_or_b64 exec, exec, s[0:1]
	s_mov_b32 s61, s69
	v_lshl_add_u64 v[20:21], v[114:115], 0, s[60:61]
	s_waitcnt lgkmcnt(0)
	s_barrier
	ds_read_b64 v[22:23], v140 offset:57344
	v_add_u32_e32 v24, s74, v135
	v_ashrrev_i32_e32 v25, 31, v24
	v_lshlrev_b64 v[24:25], 11, v[24:25]
	s_waitcnt vmcnt(7)
	v_lshlrev_b32_e32 v26, 16, v126
	s_waitcnt lgkmcnt(0)
	v_add_f32_e32 v22, v22, v23
	v_fmamk_f32 v22, v22, 0x3c000000, v147
	v_mul_f32_e32 v23, 0x4b800000, v22
	v_cmp_gt_f32_e64 s[0:1], s72, v22
	v_and_b32_e32 v27, 0xffff0000, v126
	v_lshlrev_b32_e32 v28, 16, v127
	v_cndmask_b32_e64 v22, v22, v23, s[0:1]
	v_rsq_f32_e32 v30, v22
	v_lshl_add_u64 v[22:23], s[58:59], 0, v[24:25]
	v_and_b32_e32 v29, 0xffff0000, v127
	v_mov_b32_e32 v119, v97
	v_mul_f32_e32 v24, 0x45800000, v30
	v_cndmask_b32_e64 v24, v30, v24, s[0:1]
	v_pk_mul_f32 v[16:17], v[24:25], v[16:17] op_sel_hi:[0,1]
	v_pk_mul_f32 v[18:19], v[24:25], v[18:19] op_sel_hi:[0,1]
	v_lshl_add_u64 v[22:23], v[22:23], 0, s[68:69]
	v_lshl_add_u64 v[22:23], v[22:23], 0, v[118:119]
	v_pk_mul_f32 v[12:13], v[24:25], v[12:13] op_sel_hi:[0,1]
	v_pk_mul_f32 v[14:15], v[24:25], v[14:15] op_sel_hi:[0,1]
	v_pk_mul_f32 v[8:9], v[24:25], v[8:9] op_sel_hi:[0,1]
	v_pk_mul_f32 v[10:11], v[24:25], v[10:11] op_sel_hi:[0,1]
	v_pk_mul_f32 v[0:1], v[24:25], v[0:1] op_sel_hi:[0,1]
	v_pk_mul_f32 v[2:3], v[24:25], v[2:3] op_sel_hi:[0,1]
	s_add_i32 s2, s2, s86
	s_add_i32 s73, s73, s54
	s_add_i32 s55, s55, s70
	s_cmpk_gt_i32 s2, 0xfff
	s_waitcnt vmcnt(3)
	v_mov_b64_e32 v[4:5], v[198:199]
	v_mov_b64_e32 v[6:7], v[200:201]
	v_pk_mul_f32 v[4:5], v[4:5], v[16:17]
	v_pk_mul_f32 v[6:7], v[6:7], v[18:19]
	v_pk_mul_f32 v[4:5], v[4:5], v[26:27]
	v_pk_mul_f32 v[6:7], v[6:7], v[28:29]
	v_cvt_pk_bf16_f32 v4, v4, v5
	v_cvt_pk_bf16_f32 v5, v6, v7
	global_store_dwordx2 v[22:23], v[4:5], off
	v_lshlrev_b32_e32 v16, 16, v124
	v_and_b32_e32 v17, 0xffff0000, v124
	v_lshlrev_b32_e32 v18, 16, v125
	v_and_b32_e32 v19, 0xffff0000, v125
	s_waitcnt vmcnt(3)
	v_mov_b64_e32 v[4:5], v[202:203]
	v_mov_b64_e32 v[6:7], v[204:205]
	v_pk_mul_f32 v[4:5], v[4:5], v[12:13]
	v_pk_mul_f32 v[6:7], v[6:7], v[14:15]
	v_pk_mul_f32 v[4:5], v[4:5], v[16:17]
	v_pk_mul_f32 v[6:7], v[6:7], v[18:19]
	v_cvt_pk_bf16_f32 v4, v4, v5
	v_cvt_pk_bf16_f32 v5, v6, v7
	global_store_dwordx2 v[22:23], v[4:5], off offset:32
	v_lshlrev_b32_e32 v12, 16, v122
	v_and_b32_e32 v13, 0xffff0000, v122
	v_lshlrev_b32_e32 v14, 16, v123
	v_and_b32_e32 v15, 0xffff0000, v123
	s_waitcnt vmcnt(3)
	v_mov_b64_e32 v[4:5], v[208:209]
	v_mov_b64_e32 v[6:7], v[210:211]
	v_pk_mul_f32 v[4:5], v[4:5], v[8:9]
	v_pk_mul_f32 v[6:7], v[6:7], v[10:11]
	v_pk_mul_f32 v[4:5], v[4:5], v[12:13]
	v_pk_mul_f32 v[6:7], v[6:7], v[14:15]
	v_cvt_pk_bf16_f32 v4, v4, v5
	v_cvt_pk_bf16_f32 v5, v6, v7
	global_store_dwordx2 v[22:23], v[4:5], off offset:64
	v_lshlrev_b32_e32 v8, 16, v120
	v_and_b32_e32 v9, 0xffff0000, v120
	v_lshlrev_b32_e32 v10, 16, v121
	v_and_b32_e32 v11, 0xffff0000, v121
	s_waitcnt vmcnt(3)
	v_mov_b64_e32 v[4:5], v[212:213]
	v_mov_b64_e32 v[6:7], v[214:215]
	v_pk_mul_f32 v[0:1], v[4:5], v[0:1]
	v_pk_mul_f32 v[2:3], v[6:7], v[2:3]
	v_pk_mul_f32 v[0:1], v[0:1], v[8:9]
	v_pk_mul_f32 v[2:3], v[2:3], v[10:11]
	v_cvt_pk_bf16_f32 v0, v0, v1
	v_cvt_pk_bf16_f32 v1, v2, v3
	global_store_dwordx2 v[22:23], v[0:1], off offset:96
	s_barrier
	s_cbranch_scc1 .LBB0_993

.LBB0_991:
	s_or_b64 exec, exec, s[0:1]
	s_mov_b32 s61, s69
	v_lshl_add_u64 v[188:189], v[114:115], 0, s[60:61]
	global_load_dwordx4 v[198:201], v[188:189], off
	global_load_dwordx4 v[202:205], v[188:189], off offset:64
	global_load_dwordx4 v[208:211], v[188:189], off offset:128
	global_load_dwordx4 v[212:215], v[188:189], off offset:192
	s_waitcnt vmcnt(23)
	v_mfma_f32_16x16x32_bf16 v[8:11], v[8:11], v[76:79], v[84:87]
	s_waitcnt vmcnt(22)
	v_mfma_f32_16x16x32_bf16 v[8:11], v[12:15], v[72:75], v[8:11]
	s_waitcnt vmcnt(21) lgkmcnt(1)
	v_mfma_f32_16x16x32_bf16 v[8:11], v[16:19], v[68:71], v[8:11]
	s_waitcnt vmcnt(20) lgkmcnt(0)
	v_mfma_f32_16x16x32_bf16 v[16:19], v[20:23], v[64:67], v[8:11]
	s_waitcnt vmcnt(19)
	v_mfma_f32_16x16x32_bf16 v[8:11], v[32:35], v[76:79], v[88:91]
	s_waitcnt vmcnt(18)
	v_mfma_f32_16x16x32_bf16 v[8:11], v[36:39], v[72:75], v[8:11]
	s_nop 3
	v_mul_f32_e32 v32, v17, v17
	v_fmac_f32_e32 v32, v16, v16
	v_fmac_f32_e32 v32, v18, v18
	s_waitcnt vmcnt(17)
	v_mfma_f32_16x16x32_bf16 v[8:11], v[40:43], v[68:71], v[8:11]
	v_fmac_f32_e32 v32, v19, v19
	s_waitcnt vmcnt(16)
	v_mfma_f32_16x16x32_bf16 v[12:15], v[44:47], v[64:67], v[8:11]
	s_waitcnt vmcnt(15)
	v_mfma_f32_16x16x32_bf16 v[8:11], v[48:51], v[76:79], v[92:95]
	s_waitcnt vmcnt(14)
	v_mfma_f32_16x16x32_bf16 v[8:11], v[52:55], v[72:75], v[8:11]
	s_nop 3
	v_fmac_f32_e32 v32, v12, v12
	v_fmac_f32_e32 v32, v13, v13
	v_fmac_f32_e32 v32, v14, v14
	s_waitcnt vmcnt(11)
	v_mfma_f32_16x16x32_bf16 v[20:23], v[28:31], v[76:79], v[80:83]
	v_fmac_f32_e32 v32, v15, v15
	v_mfma_f32_16x16x32_bf16 v[8:11], v[56:59], v[68:71], v[8:11]
	s_waitcnt vmcnt(10)
	v_mfma_f32_16x16x32_bf16 v[20:23], v[24:27], v[72:75], v[20:23]
	v_mfma_f32_16x16x32_bf16 v[8:11], v[60:63], v[64:67], v[8:11]
	s_waitcnt vmcnt(9)
	v_mfma_f32_16x16x32_bf16 v[4:7], v[4:7], v[68:71], v[20:23]
	s_waitcnt vmcnt(8)
	v_mfma_f32_16x16x32_bf16 v[0:3], v[0:3], v[64:67], v[4:7]
	s_nop 3
	v_fmac_f32_e32 v32, v8, v8
	v_fmac_f32_e32 v32, v9, v9
	v_fmac_f32_e32 v32, v10, v10
	v_fmac_f32_e32 v32, v11, v11
	v_fmac_f32_e32 v32, v0, v0
	v_fmac_f32_e32 v32, v1, v1
	v_fmac_f32_e32 v32, v2, v2
	v_fmac_f32_e32 v32, v3, v3
	ds_bpermute_b32 v4, v138, v32
	s_waitcnt lgkmcnt(0)
	v_add_f32_e32 v4, v32, v4
	ds_bpermute_b32 v5, v139, v4
	s_and_saveexec_b64 s[0:1], s[12:13]
	s_cbranch_execz .LBB0_978
	s_waitcnt lgkmcnt(0)
	v_add_f32_e32 v4, v4, v5
	ds_write_b32 v141, v4 offset:57344
	s_branch .LBB0_978
